# KIND0 attention loop: S accumulators via MFMA C=0 (no v_mov zeroing), leading K/V fragment ds_reads hoisted, row-max tree without canonicalising v_max
# speedup vs baseline: 1.0215x; 1.0031x over previous
.LBB0_544:
	s_bitcmp1_b32 s30, 0
	s_cselect_b32 s101, 0xa000, 0
	v_or_b32_e32 v66, s101, v156
	v_add_u32_e32 v167, v66, v158
	v_add_u32_e32 v192, v66, v159
	v_add_u32_e32 v193, v66, v160
	v_add_u32_e32 v194, v66, v161
	ds_read_b128 v[168:171], v167 offset:0
	ds_read_b128 v[172:175], v167 offset:8192
	ds_read_b128 v[176:179], v192 offset:0
	ds_read_b128 v[180:183], v192 offset:8192
	ds_read_b128 v[184:187], v193 offset:0
	ds_read_b128 v[188:191], v193 offset:8192
	s_add_i32 s23, s30, 1
	s_cmp_lt_u32 s23, s27
	s_cselect_b64 s[20:21], -1, 0
	s_cmp_ge_u32 s23, s27
	s_cbranch_scc1 .LBB0_546
	s_add_i32 s31, s22, s30
	s_cmp_lt_u32 s30, 3
	s_cselect_b32 s31, s23, s31
	s_lshl_b32 s40, s31, 6
	s_add_i32 s31, s40, s26
	v_add_u32_e32 v66, s31, v150
	v_ashrrev_i32_e32 v67, 31, v66
	v_add_u32_e32 v68, s31, v151
	v_lshlrev_b64 v[66:67], 12, v[66:67]
	v_ashrrev_i32_e32 v69, 31, v68
	s_ashr_i32 s41, s40, 31
	v_lshl_add_u64 v[66:67], v[140:141], 0, v[66:67]
	v_lshlrev_b64 v[68:69], 12, v[68:69]
	s_lshl_b64 s[40:41], s[40:41], 1
	v_lshl_add_u64 v[68:69], v[142:143], 0, v[68:69]
	global_load_dwordx4 v[114:117], v[66:67], off offset:2048
	global_load_dwordx4 v[118:121], v[68:69], off offset:2048
	v_lshl_add_u64 v[66:67], v[136:137], 0, s[40:41]
	v_lshl_add_u64 v[68:69], v[138:139], 0, s[40:41]
	global_load_dwordx4 v[122:125], v[66:67], off
	global_load_dwordx4 v[126:129], v[68:69], off
.LBB0_546:
	s_bitcmp1_b32 s30, 0
	s_mov_b32 s66, s52
	s_mov_b32 s67, s52
	s_cselect_b32 s30, 0xa000, 0
	s_mov_b32 s53, s52
	s_mov_b32 s54, s52
	s_mov_b32 s55, s52
	s_mov_b32 s56, s52
	s_mov_b32 s57, s52
	s_mov_b32 s58, s52
	s_mov_b32 s59, s52
	s_mov_b32 s60, s52
	s_mov_b32 s61, s52
	s_mov_b32 s62, s52
	s_mov_b32 s63, s52
	s_mov_b32 s64, s52
	s_mov_b32 s65, s52
	s_waitcnt lgkmcnt(5)
	v_mfma_f32_32x32x16_bf16 v[82:97], v[168:171], v[98:101], 0
	ds_read_b128 v[168:171], v194 offset:0
	s_waitcnt lgkmcnt(5)
	v_mfma_f32_32x32x16_bf16 v[66:81], v[172:175], v[98:101], 0
	ds_read_b128 v[172:175], v194 offset:8192
	s_waitcnt lgkmcnt(5)
	v_mfma_f32_32x32x16_bf16 v[82:97], v[176:179], v[102:105], v[82:97]
	s_waitcnt lgkmcnt(4)
	v_mfma_f32_32x32x16_bf16 v[66:81], v[180:183], v[102:105], v[66:81]
	s_waitcnt lgkmcnt(3)
	v_mfma_f32_32x32x16_bf16 v[82:97], v[184:187], v[106:109], v[82:97]
	s_waitcnt lgkmcnt(2)
	v_mfma_f32_32x32x16_bf16 v[66:81], v[188:191], v[106:109], v[66:81]
	s_waitcnt lgkmcnt(1)
	v_mfma_f32_32x32x16_bf16 v[82:97], v[168:171], v[110:113], v[82:97]
	s_waitcnt lgkmcnt(0)
	v_mfma_f32_32x32x16_bf16 v[66:81], v[172:175], v[110:113], v[66:81]
	s_nop 15
	s_nop 3

	v_add_u32_e32 v195, s30, v157
	v_add_u32_e32 v196, v195, v162
	v_add_u32_e32 v197, v195, v163
	ds_read_b128 v[228:231], v196 offset:0
	ds_read_b128 v[232:235], v196 offset:4096
	ds_read_b128 v[236:239], v196 offset:8192
	ds_read_b128 v[240:243], v196 offset:12288
	ds_read_b128 v[244:247], v197 offset:0
	ds_read_b128 v[248:251], v197 offset:4096
	s_mov_b32 s4, 0xf149f2ca
	v_max3_f32 v167, v82, v83, s4
	v_max3_f32 v168, v84, v85, v86
	v_max3_f32 v169, v87, v88, v89
	v_max3_f32 v170, v90, v91, v92
	v_max3_f32 v167, v167, v93, v94
	v_max3_f32 v168, v168, v95, v96
	v_max3_f32 v169, v169, v97, v66
	v_max3_f32 v170, v170, v67, v68
	v_max3_f32 v167, v167, v69, v70
	v_max3_f32 v168, v168, v71, v72
	v_max3_f32 v169, v169, v73, v74
	v_max3_f32 v170, v170, v75, v76
	v_max3_f32 v167, v167, v77, v78
	v_max3_f32 v168, v168, v79, v80
	v_max3_f32 v169, v169, v81, v170
	v_max3_f32 v167, v167, v168, v169
	v_mov_b32_e32 v168, v167
	s_nop 1
	v_permlane32_swap_b32_e32 v167, v168
	v_max3_f32 v167, v130, v167, v168
	v_mul_f32_e32 v171, 0xbe38aa3b, v167
	v_fmamk_f32 v82, v82, 0x3e38aa3b, v171
	v_exp_f32_e32 v82, v82
	v_fmamk_f32 v83, v83, 0x3e38aa3b, v171
	v_exp_f32_e32 v83, v83
	v_fmamk_f32 v84, v84, 0x3e38aa3b, v171
	v_exp_f32_e32 v84, v84
	v_fmamk_f32 v85, v85, 0x3e38aa3b, v171
	v_exp_f32_e32 v85, v85
	v_fmamk_f32 v86, v86, 0x3e38aa3b, v171
	v_add_f32_e32 v168, 0, v82
	v_exp_f32_e32 v86, v86
	v_fmamk_f32 v87, v87, 0x3e38aa3b, v171
	v_add_f32_e32 v168, v83, v168
	v_exp_f32_e32 v87, v87
	v_fmamk_f32 v88, v88, 0x3e38aa3b, v171
	v_add_f32_e32 v168, v84, v168
	v_exp_f32_e32 v88, v88
	v_fmamk_f32 v89, v89, 0x3e38aa3b, v171
	v_add_f32_e32 v169, v85, v168
	v_exp_f32_e32 v168, v89
	v_add_f32_e32 v89, v86, v169
	v_add_f32_e32 v89, v87, v89
	v_add_f32_e32 v89, v88, v89
	v_add_f32_e32 v169, v168, v89
	v_fmamk_f32 v89, v90, 0x3e38aa3b, v171
	v_exp_f32_e32 v89, v89
	v_fmamk_f32 v90, v91, 0x3e38aa3b, v171
	v_exp_f32_e32 v90, v90
	v_fmamk_f32 v91, v92, 0x3e38aa3b, v171
	v_exp_f32_e32 v91, v91
	v_fmamk_f32 v92, v93, 0x3e38aa3b, v171
	v_exp_f32_e32 v92, v92
	v_add_f32_e32 v93, v89, v169
	v_add_f32_e32 v93, v90, v93
	v_add_f32_e32 v93, v91, v93
	v_add_f32_e32 v169, v92, v93
	v_fmamk_f32 v93, v94, 0x3e38aa3b, v171
	v_exp_f32_e32 v93, v93
	v_fmamk_f32 v94, v95, 0x3e38aa3b, v171
	v_exp_f32_e32 v94, v94
	v_fmamk_f32 v95, v96, 0x3e38aa3b, v171
	v_exp_f32_e32 v95, v95
	v_fmamk_f32 v96, v97, 0x3e38aa3b, v171
	v_exp_f32_e32 v97, v96
	v_add_f32_e32 v96, v93, v169
	v_add_f32_e32 v96, v94, v96
	v_add_f32_e32 v96, v95, v96
	v_fmamk_f32 v66, v66, 0x3e38aa3b, v171
	v_add_f32_e32 v170, v97, v96
	v_exp_f32_e32 v96, v66
	v_fmamk_f32 v66, v67, 0x3e38aa3b, v171
	v_exp_f32_e32 v169, v66
	v_fmamk_f32 v66, v68, 0x3e38aa3b, v171
	v_exp_f32_e32 v68, v66
	v_fmamk_f32 v66, v69, 0x3e38aa3b, v171
	v_exp_f32_e32 v69, v66
	v_fmamk_f32 v67, v70, 0x3e38aa3b, v171
	v_add_f32_e32 v66, v96, v170
	v_exp_f32_e32 v70, v67
	v_fmamk_f32 v67, v71, 0x3e38aa3b, v171
	v_add_f32_e32 v66, v169, v66
	v_exp_f32_e32 v71, v67
	v_fmamk_f32 v67, v72, 0x3e38aa3b, v171
	v_add_f32_e32 v66, v68, v66
	v_exp_f32_e32 v72, v67
	v_fmamk_f32 v67, v73, 0x3e38aa3b, v171
	v_add_f32_e32 v66, v69, v66
	v_exp_f32_e32 v170, v67
	v_fmamk_f32 v67, v74, 0x3e38aa3b, v171
	v_add_f32_e32 v66, v70, v66
	v_exp_f32_e32 v73, v67
	v_fmamk_f32 v67, v75, 0x3e38aa3b, v171
	v_add_f32_e32 v66, v71, v66
	v_exp_f32_e32 v74, v67
	v_fmamk_f32 v67, v76, 0x3e38aa3b, v171
	v_add_f32_e32 v66, v72, v66
	v_exp_f32_e32 v75, v67
	v_fmamk_f32 v67, v77, 0x3e38aa3b, v171
	v_add_f32_e32 v66, v170, v66
	v_exp_f32_e32 v76, v67
	v_fmamk_f32 v67, v78, 0x3e38aa3b, v171
	v_add_f32_e32 v66, v73, v66
	v_exp_f32_e32 v77, v67
	v_fmamk_f32 v67, v79, 0x3e38aa3b, v171
	v_add_f32_e32 v66, v74, v66
	v_exp_f32_e32 v78, v67
	v_fmamk_f32 v67, v80, 0x3e38aa3b, v171
	v_add_f32_e32 v66, v75, v66
	v_exp_f32_e32 v79, v67
	v_fmac_f32_e32 v171, 0x3e38aa3b, v81
	v_sub_f32_e32 v130, v130, v167
	v_add_f32_e32 v66, v76, v66
	v_exp_f32_e32 v80, v171
	v_mul_f32_e32 v130, 0x3e38aa3b, v130
	v_add_f32_e32 v66, v77, v66
	v_exp_f32_e32 v130, v130
	v_add_f32_e32 v66, v78, v66
	v_add_f32_e32 v66, v79, v66
	v_add_f32_e32 v66, v80, v66
	v_mov_b32_e32 v67, v66
	s_nop 1
	v_permlane32_swap_b32_e32 v66, v67
	v_cmp_neq_f32_e32 vcc, 1.0, v130
	s_cbranch_vccz .LBB0_548
	v_pk_mul_f32 v[64:65], v[64:65], v[130:131] op_sel_hi:[1,0]
	v_pk_mul_f32 v[62:63], v[62:63], v[130:131] op_sel_hi:[1,0]
	v_pk_mul_f32 v[60:61], v[60:61], v[130:131] op_sel_hi:[1,0]
	v_pk_mul_f32 v[58:59], v[58:59], v[130:131] op_sel_hi:[1,0]
	v_pk_mul_f32 v[56:57], v[56:57], v[130:131] op_sel_hi:[1,0]
	v_pk_mul_f32 v[54:55], v[54:55], v[130:131] op_sel_hi:[1,0]
	v_pk_mul_f32 v[52:53], v[52:53], v[130:131] op_sel_hi:[1,0]
	v_pk_mul_f32 v[50:51], v[50:51], v[130:131] op_sel_hi:[1,0]
	v_pk_mul_f32 v[48:49], v[48:49], v[130:131] op_sel_hi:[1,0]
	v_pk_mul_f32 v[46:47], v[46:47], v[130:131] op_sel_hi:[1,0]
	v_pk_mul_f32 v[44:45], v[44:45], v[130:131] op_sel_hi:[1,0]
	v_pk_mul_f32 v[42:43], v[42:43], v[130:131] op_sel_hi:[1,0]
	v_pk_mul_f32 v[40:41], v[40:41], v[130:131] op_sel_hi:[1,0]
	v_pk_mul_f32 v[38:39], v[38:39], v[130:131] op_sel_hi:[1,0]
	v_pk_mul_f32 v[36:37], v[36:37], v[130:131] op_sel_hi:[1,0]
	v_pk_mul_f32 v[34:35], v[34:35], v[130:131] op_sel_hi:[1,0]
	v_pk_mul_f32 v[32:33], v[32:33], v[130:131] op_sel_hi:[1,0]
	v_pk_mul_f32 v[30:31], v[30:31], v[130:131] op_sel_hi:[1,0]
	v_pk_mul_f32 v[28:29], v[28:29], v[130:131] op_sel_hi:[1,0]
	v_pk_mul_f32 v[26:27], v[26:27], v[130:131] op_sel_hi:[1,0]
	v_pk_mul_f32 v[24:25], v[24:25], v[130:131] op_sel_hi:[1,0]
	v_pk_mul_f32 v[22:23], v[22:23], v[130:131] op_sel_hi:[1,0]
	v_pk_mul_f32 v[20:21], v[20:21], v[130:131] op_sel_hi:[1,0]
	v_pk_mul_f32 v[18:19], v[18:19], v[130:131] op_sel_hi:[1,0]
	v_pk_mul_f32 v[16:17], v[16:17], v[130:131] op_sel_hi:[1,0]
	v_pk_mul_f32 v[14:15], v[14:15], v[130:131] op_sel_hi:[1,0]
	v_pk_mul_f32 v[12:13], v[12:13], v[130:131] op_sel_hi:[1,0]
	v_pk_mul_f32 v[10:11], v[10:11], v[130:131] op_sel_hi:[1,0]
	v_pk_mul_f32 v[8:9], v[8:9], v[130:131] op_sel_hi:[1,0]
	v_pk_mul_f32 v[6:7], v[6:7], v[130:131] op_sel_hi:[1,0]
	v_pk_mul_f32 v[4:5], v[4:5], v[130:131] op_sel_hi:[1,0]
	v_pk_mul_f32 v[2:3], v[2:3], v[130:131] op_sel_hi:[1,0]
.LBB0_548:
	v_add_u32_e32 v81, s30, v157
	v_cvt_pk_bf16_f32 v82, v82, v83
	v_cvt_pk_bf16_f32 v83, v84, v85
	v_cvt_pk_bf16_f32 v84, v86, v87
	v_cvt_pk_bf16_f32 v85, v88, v168
	v_cvt_pk_bf16_f32 v86, v89, v90
	v_cvt_pk_bf16_f32 v87, v91, v92
	v_cvt_pk_bf16_f32 v88, v93, v94
	v_cvt_pk_bf16_f32 v89, v95, v97
	v_cvt_pk_bf16_f32 v90, v96, v169
	v_cvt_pk_bf16_f32 v91, v68, v69
	v_cvt_pk_bf16_f32 v92, v70, v71
	v_cvt_pk_bf16_f32 v93, v72, v170
	v_cvt_pk_bf16_f32 v68, v73, v74
	v_cvt_pk_bf16_f32 v69, v75, v76
	v_cvt_pk_bf16_f32 v70, v77, v78
	v_cvt_pk_bf16_f32 v71, v79, v80
	v_add_u32_e32 v80, v81, v162
	v_add_u32_e32 v180, v81, v163
	v_add_u32_e32 v181, v81, v164
	v_add_u32_e32 v81, v81, v165
	s_waitcnt lgkmcnt(5)
	v_mfma_f32_32x32x16_bf16 v[50:65], v[228:231], v[82:85], v[50:65]
	ds_read_b128 v[72:75], v180 offset:8192
	s_waitcnt lgkmcnt(5)
	v_mfma_f32_32x32x16_bf16 v[34:49], v[232:235], v[82:85], v[34:49]
	ds_read_b128 v[76:79], v180 offset:12288
	s_waitcnt lgkmcnt(5)
	v_mfma_f32_32x32x16_bf16 v[18:33], v[236:239], v[82:85], v[18:33]
	ds_read_b128 v[94:97], v181 offset:0
	s_waitcnt lgkmcnt(5)
	v_mfma_f32_32x32x16_bf16 v[2:17], v[240:243], v[82:85], v[2:17]
	ds_read_b128 v[168:171], v181 offset:4096
	s_waitcnt lgkmcnt(5)
	v_mfma_f32_32x32x16_bf16 v[50:65], v[244:247], v[86:89], v[50:65]
	ds_read_b128 v[172:175], v181 offset:8192
	s_waitcnt lgkmcnt(5)
	v_mfma_f32_32x32x16_bf16 v[34:49], v[248:251], v[86:89], v[34:49]
	ds_read_b128 v[176:179], v181 offset:12288
	s_waitcnt lgkmcnt(5)
	v_mfma_f32_32x32x16_bf16 v[18:33], v[72:75], v[86:89], v[18:33]
	ds_read_b128 v[72:75], v81 offset:0
	s_waitcnt lgkmcnt(5)
	v_mfma_f32_32x32x16_bf16 v[2:17], v[76:79], v[86:89], v[2:17]
	ds_read_b128 v[76:79], v81 offset:4096
	s_waitcnt lgkmcnt(5)
	v_mfma_f32_32x32x16_bf16 v[50:65], v[94:97], v[90:93], v[50:65]
	ds_read_b128 v[94:97], v81 offset:8192
	s_waitcnt lgkmcnt(5)
	v_mfma_f32_32x32x16_bf16 v[34:49], v[168:171], v[90:93], v[34:49]
	ds_read_b128 v[168:171], v81 offset:12288
	s_waitcnt lgkmcnt(5)
	v_mfma_f32_32x32x16_bf16 v[18:33], v[172:175], v[90:93], v[18:33]
	s_waitcnt lgkmcnt(4)
	v_mfma_f32_32x32x16_bf16 v[2:17], v[176:179], v[90:93], v[2:17]
	s_waitcnt lgkmcnt(3)
	v_mfma_f32_32x32x16_bf16 v[50:65], v[72:75], v[68:71], v[50:65]
	s_waitcnt lgkmcnt(2)
	v_mfma_f32_32x32x16_bf16 v[34:49], v[76:79], v[68:71], v[34:49]
	s_waitcnt lgkmcnt(1)
	v_mfma_f32_32x32x16_bf16 v[18:33], v[94:97], v[68:71], v[18:33]
	s_waitcnt lgkmcnt(0)
	v_mfma_f32_32x32x16_bf16 v[2:17], v[168:171], v[68:71], v[2:17]
	s_nop 15
	s_nop 3

	s_andn2_b64 vcc, exec, s[20:21]
	s_movk_i32 s66, 0xff
	v_readlane_b32 s54, v255, 3
	v_readlane_b32 s55, v255, 4
	s_cbranch_vccnz .LBB0_550
	s_bitcmp1_b32 s23, 0
	s_cselect_b32 s20, 0xa000, 0
	v_add_u32_e32 v68, s20, v152
	v_add_u32_e32 v69, s20, v153
	v_add_u32_e32 v70, s20, v154
	v_add_u32_e32 v71, s20, v155
	s_waitcnt vmcnt(3)
	ds_write_b128 v68, v[114:117]
	s_waitcnt vmcnt(2)
	ds_write_b128 v69, v[118:121]
	s_waitcnt vmcnt(1)
	ds_write_b128 v70, v[122:125] offset:24576
	s_waitcnt vmcnt(0)
	ds_write_b128 v71, v[126:129] offset:24576

	.amdhsa_kernel _Z4mega6Params
		.amdhsa_group_segment_fixed_size 138256
		.amdhsa_private_segment_fixed_size 0
		.amdhsa_kernarg_size 2024
		.amdhsa_user_sgpr_count 2
		.amdhsa_user_sgpr_dispatch_ptr 0
		.amdhsa_user_sgpr_queue_ptr 0
		.amdhsa_user_sgpr_kernarg_segment_ptr 1
		.amdhsa_user_sgpr_dispatch_id 0
		.amdhsa_user_sgpr_kernarg_preload_length 0
		.amdhsa_user_sgpr_kernarg_preload_offset 0
		.amdhsa_user_sgpr_private_segment_size 0
		.amdhsa_uses_dynamic_stack 0
		.amdhsa_enable_private_segment 0
		.amdhsa_system_sgpr_workgroup_id_x 1
		.amdhsa_system_sgpr_workgroup_id_y 0
		.amdhsa_system_sgpr_workgroup_id_z 0
		.amdhsa_system_sgpr_workgroup_info 0
		.amdhsa_system_vgpr_workitem_id 2
		.amdhsa_next_free_vgpr 256
		.amdhsa_next_free_sgpr 102
		.amdhsa_accum_offset 256
		.amdhsa_reserve_vcc 1
		.amdhsa_float_round_mode_32 0
		.amdhsa_float_round_mode_16_64 0
		.amdhsa_float_denorm_mode_32 3
		.amdhsa_float_denorm_mode_16_64 3
		.amdhsa_dx10_clamp 1
		.amdhsa_ieee_mode 1
		.amdhsa_fp16_overflow 0
		.amdhsa_tg_split 0
		.amdhsa_exception_fp_ieee_invalid_op 0
		.amdhsa_exception_fp_denorm_src 0
		.amdhsa_exception_fp_ieee_div_zero 0
		.amdhsa_exception_fp_ieee_overflow 0
		.amdhsa_exception_fp_ieee_underflow 0
		.amdhsa_exception_fp_ieee_inexact 0
		.amdhsa_exception_int_div_zero 0
	.end_amdhsa_kernel

amdhsa.kernels:
  - .agpr_count:     0
    .args:
      - .offset:         0
        .size:           1768
        .value_kind:     by_value
      - .offset:         1768
        .size:           4
        .value_kind:     hidden_block_count_x
      - .offset:         1772
        .size:           4
        .value_kind:     hidden_block_count_y
      - .offset:         1776
        .size:           4
        .value_kind:     hidden_block_count_z
      - .offset:         1780
        .size:           2
        .value_kind:     hidden_group_size_x
      - .offset:         1782
        .size:           2
        .value_kind:     hidden_group_size_y
      - .offset:         1784
        .size:           2
        .value_kind:     hidden_group_size_z
      - .offset:         1786
        .size:           2
        .value_kind:     hidden_remainder_x
      - .offset:         1788
        .size:           2
        .value_kind:     hidden_remainder_y
      - .offset:         1790
        .size:           2
        .value_kind:     hidden_remainder_z
      - .offset:         1808
        .size:           8
        .value_kind:     hidden_global_offset_x
      - .offset:         1816
        .size:           8
        .value_kind:     hidden_global_offset_y
      - .offset:         1824
        .size:           8
        .value_kind:     hidden_global_offset_z
      - .offset:         1832
        .size:           2
        .value_kind:     hidden_grid_dims
      - .offset:         1856
        .size:           8
        .value_kind:     hidden_multigrid_sync_arg
    .group_segment_fixed_size: 138256
    .kernarg_segment_align: 8
    .kernarg_segment_size: 2024
    .language:       OpenCL C
    .language_version:
      - 2
      - 0
    .max_flat_workgroup_size: 512
    .name:           _Z4mega6Params
    .private_segment_fixed_size: 0
    .sgpr_count:     108
    .sgpr_spill_count: 135
    .symbol:         _Z4mega6Params.kd
    .uniform_work_group_size: 1
    .uses_dynamic_stack: false
    .vgpr_count:     256
    .vgpr_spill_count: 0
    .wavefront_size: 64
